# P0 memory-row rms-norm rows moved to waves 1280..1791 (one gu1 transpose item) on top of the P3 tail rebalance
# speedup vs baseline: 1.0024x; 1.0024x over previous
; DI void rms_row_to_bf16(const float* xrow, const float* gain, bf16_t* orow, int lane) {
;     const f32x4* xr = (const f32x4*)xrow + lane;
;     f32x4 v[4]; float s = 0.f;
; #pragma unroll
;     for (int jj = 0; jj < 4; ++jj) { v[jj] = xr[64 * jj]; s += (v[jj][0] * v[jj][0] + v[jj][1] * v[jj][1]) + (v[jj][2] * v[jj][2] + v[jj][3] * v[jj][3]); }
;     const float rstd = 1.0f / sqrtf(wave_sum(s) * (1.0f / 1024.0f) + EPS);
; __global__ void __launch_bounds__(512, 2) fwd_mega(Args args) {
;     ...
;         for (int m = gw; m < 512; m += ngw) rms_row_to_bf16(mem + (size_t)m * DM, args.in[19], MEMN + (size_t)m * DM, lane);
.LBB0_239:
	v_readlane_b32 s98, v249, 54
	s_add_i32 s100, s98, 0xfffffb00
	s_and_b32 s100, s100, 0x7ff
	s_cmpk_eq_i32 s86, 0x100
	s_cselect_b32 s100, s100, s98
	s_cmpk_gt_i32 s100, 0x1ff
	s_cbranch_scc1 .LBB0_250
	v_mbcnt_lo_u32_b32 v0, -1, 0
	v_mbcnt_hi_u32_b32 v0, -1, v0
	v_and_b32_e32 v1, 64, v0
	v_add_u32_e32 v1, 64, v1
	v_xor_b32_e32 v2, 1, v0
	v_cmp_lt_i32_e32 vcc, v2, v1
	s_cmp_lg_u64 s[58:59], 0
	v_readlane_b32 s4, v249, 54
	v_cndmask_b32_e32 v2, v0, v2, vcc
	v_lshlrev_b32_e32 v30, 2, v2
	v_xor_b32_e32 v2, 2, v0
	v_cmp_lt_i32_e32 vcc, v2, v1
	s_cselect_b64 s[2:3], -1, 0
	v_readlane_b32 s5, v249, 55
	v_cndmask_b32_e32 v2, v0, v2, vcc
	v_lshlrev_b32_e32 v31, 2, v2
	v_xor_b32_e32 v2, 4, v0
	v_cmp_lt_i32_e32 vcc, v2, v1
	s_mov_b32 s14, s100
	s_ashr_i32 s15, s100, 31
	v_cndmask_b32_e32 v2, v0, v2, vcc
	v_lshlrev_b32_e32 v34, 2, v2
	v_xor_b32_e32 v2, 8, v0
	v_cmp_lt_i32_e32 vcc, v2, v1
	s_lshl_b64 s[4:5], s[14:15], 11
	v_mov_b32_e32 v33, 0
	v_cndmask_b32_e32 v2, v0, v2, vcc
	v_lshlrev_b32_e32 v35, 2, v2
	v_xor_b32_e32 v2, 16, v0
	v_cmp_lt_i32_e32 vcc, v2, v1
	s_add_u32 s4, s8, s4
	s_addc_u32 s5, s9, s5
	v_cndmask_b32_e32 v2, v0, v2, vcc
	v_lshlrev_b32_e32 v36, 2, v2
	v_xor_b32_e32 v2, 32, v0
	v_cmp_lt_i32_e32 vcc, v2, v1
	v_mov_b32_e32 v1, v33
	s_ashr_i32 s89, s88, 31
	v_cndmask_b32_e32 v0, v0, v2, vcc
	v_lshlrev_b32_e32 v37, 2, v0
	v_lshlrev_b32_e32 v0, 3, v128
	v_lshl_add_u64 v[0:1], s[4:5], 0, v[0:1]
	s_mov_b64 s[4:5], 0x3f00000
	v_readlane_b32 s36, v249, 17
	v_lshl_add_u64 v[24:25], v[0:1], 0, s[4:5]
	s_lshl_b64 s[6:7], s[88:89], 11
	s_lshl_b64 s[4:5], s[14:15], 12
	v_readlane_b32 s38, v249, 19
	v_readlane_b32 s39, v249, 20
	s_add_u32 s4, s38, s4
	s_addc_u32 s5, s39, s5
	v_lshl_add_u64 v[0:1], s[4:5], 0, v[32:33]
	s_mov_b64 s[4:5], 0x800
	v_lshl_add_u64 v[26:27], v[0:1], 0, s[4:5]
	v_cndmask_b32_e64 v0, 0, 1, s[2:3]
	s_mov_b32 s4, s98
	v_lshl_add_u64 v[22:23], s[58:59], 0, v[32:33]
	v_readlane_b32 s37, v249, 18
	v_readlane_b32 s40, v249, 21
	v_readlane_b32 s41, v249, 22
	v_readlane_b32 s42, v249, 23
	v_readlane_b32 s43, v249, 24
	v_readlane_b32 s44, v249, 25
	v_readlane_b32 s45, v249, 26
	v_readlane_b32 s46, v249, 27
	v_readlane_b32 s47, v249, 28
	v_readlane_b32 s48, v249, 29
	v_readlane_b32 s49, v249, 30
	v_readlane_b32 s50, v249, 31
	v_readlane_b32 s51, v249, 32
	s_lshl_b64 s[10:11], s[88:89], 12
	v_cmp_ne_u32_e64 s[2:3], 1, v0
	v_mov_b32_e32 v32, 0x358637bd
	s_mov_b32 s12, 0xf800000
	v_mov_b32_e32 v33, 0x260
	v_writelane_b32 v249, s4, 54
	s_mov_b32 s13, s14
	s_nop 0
	v_writelane_b32 v249, s5, 55
	s_branch .LBB0_242
